# attention MODE0 steady loop: selection bit taken by scalar bit index (v_bfe with SGPR offset) instead of shifting the 128-bit mask every step
# speedup vs baseline: 1.0034x; 1.0034x over previous
.LBB0_796:
	v_lshlrev_b32_e32 v53, 1, v52
	v_lshlrev_b32_e32 v52, 4, v52
	v_and_b32_e32 v214, 32, v53
	v_and_b32_e32 v52, 0xc0, v52
	v_lshl_or_b32 v213, v209, 8, v52
	v_add_u32_e32 v52, 0, v214
	v_add3_u32 v219, v52, v211, v213
	v_max3_f32 v52, v36, v37, v20
	v_max3_f32 v53, v38, v39, v21
	s_and_b32 s0, s22, 0x3fffffc0
	v_max3_f32 v52, v52, v22, v23
	v_max3_f32 v53, v53, v42, v43
	s_lshl_b32 s0, s0, 2
	v_max3_f32 v52, v52, v40, v41
	v_max3_f32 v53, v53, v26, v27
	s_add_i32 s1, s64, 0x100
	v_max3_f32 v52, v52, v24, v25
	v_max3_f32 v53, v53, v46, v47
	s_add_i32 s53, s0, 0
	v_max3_f32 v52, v52, v44, v45
	v_max3_f32 v53, v53, v30, v31
	s_lshr_b32 s48, s1, 6
	v_max3_f32 v52, v52, v28, v29
	v_max3_f32 v53, v53, v50, v51
	s_mov_b64 s[22:23], 0x60000
	v_max3_f32 v52, v52, v48, v49
	v_max3_f32 v53, v53, v34, v35
	s_cmp_lg_u32 0, -1
	v_max3_f32 v52, v52, v32, v33
	s_mov_b64 s[10:11], 0x20000
	v_max_f32_e32 v52, v52, v53
	v_lshl_add_u64 v[190:191], v[84:85], 0, s[10:11]
	v_mov_b32_e32 v53, v52
	s_nop 1
	v_permlane32_swap_b32_e32 v52, v53
	v_max_f32_e32 v52, v52, v53
	s_mov_b32 s0, 1
	v_max_f32_e32 v52, v52, v228
	s_mov_b32 s24, 0
	v_add_f32_e32 v217, v3, v52
	v_sub_f32_e32 v53, v36, v52
	v_sub_f32_e32 v54, v37, v52
	v_sub_f32_e32 v55, v38, v52
	v_sub_f32_e32 v56, v39, v52
	v_sub_f32_e32 v57, v40, v52
	s_nop 0
	v_xor_b32_e32 v36, 0x80000000, v217
	v_sub_f32_e32 v58, v41, v52
	v_sub_f32_e32 v59, v42, v52
	v_sub_f32_e32 v60, v43, v52
	v_sub_f32_e32 v61, v44, v52
	v_sub_f32_e32 v62, v45, v52
	v_sub_f32_e32 v63, v46, v52
	v_sub_f32_e32 v64, v47, v52
	v_sub_f32_e32 v65, v48, v52
	v_sub_f32_e32 v66, v49, v52
	v_sub_f32_e32 v67, v50, v52
	v_sub_f32_e32 v83, v51, v52
	v_mov_b32_e32 v37, v36
	v_mov_b32_e32 v38, v36
	v_mov_b32_e32 v39, v36
	v_mov_b32_e32 v40, v36
	v_mov_b32_e32 v41, v36
	v_mov_b32_e32 v42, v36
	v_mov_b32_e32 v43, v36
	v_mov_b32_e32 v44, v36
	v_mov_b32_e32 v45, v36
	v_mov_b32_e32 v46, v36
	v_mov_b32_e32 v47, v36
	v_mov_b32_e32 v48, v36
	v_mov_b32_e32 v49, v36
	v_mov_b32_e32 v50, v36
	v_mov_b32_e32 v51, v36
	v_sub_f32_e32 v20, v20, v52
	v_sub_f32_e32 v21, v21, v52
	s_waitcnt vmcnt(0) lgkmcnt(0)
	s_barrier
	v_sub_f32_e32 v22, v22, v52
	v_sub_f32_e32 v23, v23, v52
	v_sub_f32_e32 v24, v24, v52
	v_sub_f32_e32 v25, v25, v52
	v_sub_f32_e32 v26, v26, v52
	v_sub_f32_e32 v27, v27, v52
	v_sub_f32_e32 v28, v28, v52
	v_sub_f32_e32 v29, v29, v52
	v_sub_f32_e32 v30, v30, v52
	v_sub_f32_e32 v31, v31, v52
	v_sub_f32_e32 v32, v32, v52
	v_sub_f32_e32 v33, v33, v52
	v_sub_f32_e32 v34, v34, v52
	v_sub_f32_e32 v35, v35, v52
	v_exp_f32_e32 v68, v53
	v_exp_f32_e32 v52, v20
	v_exp_f32_e32 v53, v21
	v_lshl_add_u64 v[20:21], v[188:189], 0, s[22:23]
	s_mov_b32 m0, s46
	s_nop 0
	global_load_lds_dwordx4 v[20:21], off
	s_cselect_b32 s1, 0, 0
	s_add_i32 s1, s1, s45
	s_add_i32 s1, s1, 0x8000
	s_mov_b32 m0, s1
	s_nop 0
	global_load_lds_dwordx4 v[190:191], off
	ds_read_b128 v[180:183], v218 offset:8192
	ds_read_b128 v[176:179], v218 offset:8704
	ds_read_b128 v[172:175], v218 offset:10240
	ds_read_b128 v[168:171], v218 offset:10752
	ds_read_b128 v[164:167], v218 offset:12288
	ds_read_b128 v[160:163], v218 offset:12800
	ds_read_b128 v[156:159], v218 offset:14336
	ds_read_b128 v[152:155], v218 offset:14848
	v_exp_f32_e32 v69, v54
	v_exp_f32_e32 v70, v55
	v_exp_f32_e32 v71, v56
	v_exp_f32_e32 v72, v57
	v_exp_f32_e32 v73, v58
	v_exp_f32_e32 v74, v59
	v_exp_f32_e32 v75, v60
	v_exp_f32_e32 v76, v61
	v_exp_f32_e32 v77, v62
	v_exp_f32_e32 v78, v63
	v_exp_f32_e32 v79, v64
	v_exp_f32_e32 v80, v65
	v_exp_f32_e32 v81, v66
	v_exp_f32_e32 v82, v67
	v_exp_f32_e32 v83, v83
	v_exp_f32_e32 v54, v22
	v_exp_f32_e32 v55, v23
	v_exp_f32_e32 v56, v24
	v_exp_f32_e32 v57, v25
	v_exp_f32_e32 v58, v26
	v_exp_f32_e32 v59, v27
	v_exp_f32_e32 v60, v28
	v_exp_f32_e32 v61, v29
	v_exp_f32_e32 v62, v30
	v_exp_f32_e32 v63, v31
	v_exp_f32_e32 v64, v32
	v_exp_f32_e32 v65, v33
	v_exp_f32_e32 v66, v34
	v_exp_f32_e32 v67, v35
	s_waitcnt vmcnt(2) lgkmcnt(0)
	s_barrier
	s_andn2_b64 vcc, exec, s[4:5]
	v_cmp_gt_u32_e64 s[4:5], 32, v1
	s_cbranch_vccnz .LBB0_812
	v_lshlrev_b32_e32 v20, 4, v209
	s_mov_b64 s[10:11], 0xa0000
	v_add_u32_e32 v203, s53, v20
	v_mov_b64_e32 v[34:35], v[18:19]
	s_add_i32 s1, s48, -5
	v_lshl_add_u32 v202, v208, 2, s53
	v_lshl_add_u64 v[192:193], v[84:85], 0, s[22:23]
	v_lshl_add_u64 v[194:195], v[188:189], 0, s[10:11]
	s_movk_i32 s24, 0x4000
	s_movk_i32 s25, 0x2000
	s_mov_b32 s10, 0
	v_mov_b32_e32 v220, 0
	v_mov_b64_e32 v[32:33], v[16:17]
	v_mov_b64_e32 v[30:31], v[14:15]
	v_mov_b64_e32 v[28:29], v[12:13]
	v_mov_b64_e32 v[26:27], v[10:11]
	v_mov_b64_e32 v[24:25], v[8:9]
	v_mov_b64_e32 v[22:23], v[6:7]
	v_mov_b64_e32 v[20:21], v[4:5]
	s_mov_b32 s101, 0
	s_branch .LBB0_798

.LBB0_798:
	v_bfe_i32 v196, v132, s101, 1
	v_add_u32_e32 v197, s10, v219
	ds_read_b64_tr_b16 v[184:185], v197 offset:24576
	ds_read_b64_tr_b16 v[186:187], v197 offset:25088
	v_mfma_f32_32x32x16_bf16 v[100:115], v[180:183], v[116:119], v[36:51]
	v_add_f32_e32 v84, v68, v69
	v_add_f32_e32 v84, v70, v84
	v_add_f32_e32 v84, v71, v84
	v_cvt_pk_bf16_f32 v68, v68, v69
	v_add_f32_e32 v84, v72, v84
	v_and_b32_e32 v148, v68, v196
	v_cvt_pk_bf16_f32 v68, v70, v71
	v_add_f32_e32 v84, v73, v84
	v_and_b32_e32 v149, v68, v196
	ds_read_b64_tr_b16 v[180:181], v197 offset:28672
	ds_read_b64_tr_b16 v[182:183], v197 offset:29184
	v_add_f32_e32 v68, v74, v84
	v_mfma_f32_32x32x16_bf16 v[84:99], v[176:179], v[116:119], v[36:51]
	v_add_f32_e32 v68, v75, v68
	v_add_f32_e32 v68, v76, v68
	v_add_f32_e32 v136, v77, v68
	v_cvt_pk_bf16_f32 v68, v72, v73
	v_and_b32_e32 v150, v68, v196
	v_cvt_pk_bf16_f32 v68, v74, v75
	v_and_b32_e32 v151, v68, v196
	ds_read_b64_tr_b16 v[68:69], v197 offset:25600
	ds_read_b64_tr_b16 v[70:71], v197 offset:26112
	v_mfma_f32_32x32x16_bf16 v[100:115], v[172:175], v[120:123], v[100:115]
	v_add_f32_e32 v72, v78, v136
	v_add_f32_e32 v72, v79, v72
	v_add_f32_e32 v72, v80, v72
	v_add_f32_e32 v136, v81, v72
	v_cvt_pk_bf16_f32 v72, v76, v77
	v_and_b32_e32 v144, v72, v196
	v_cvt_pk_bf16_f32 v72, v78, v79
	v_and_b32_e32 v145, v72, v196
	ds_read_b64_tr_b16 v[72:73], v197 offset:29696
	ds_read_b64_tr_b16 v[74:75], v197 offset:30208
	v_mfma_f32_32x32x16_bf16 v[84:99], v[168:171], v[120:123], v[84:99]
	v_add_f32_e32 v76, v82, v136
	v_add_f32_e32 v76, v83, v76
	v_add_f32_e32 v76, v52, v76
	v_add_f32_e32 v136, v53, v76
	v_cvt_pk_bf16_f32 v76, v80, v81
	v_and_b32_e32 v146, v76, v196
	v_cvt_pk_bf16_f32 v76, v82, v83
	v_and_b32_e32 v147, v76, v196
	ds_read_b64_tr_b16 v[76:77], v197 offset:26624
	ds_read_b64_tr_b16 v[78:79], v197 offset:27136
	v_mfma_f32_32x32x16_bf16 v[100:115], v[164:167], v[124:127], v[100:115]
	v_add_f32_e32 v80, v54, v136
	v_add_f32_e32 v80, v55, v80
	v_cvt_pk_bf16_f32 v52, v52, v53
	v_add_f32_e32 v80, v56, v80
	v_and_b32_e32 v140, v52, v196
	v_cvt_pk_bf16_f32 v52, v54, v55
	v_add_f32_e32 v80, v57, v80
	v_and_b32_e32 v141, v52, v196
	ds_read_b64_tr_b16 v[52:53], v197 offset:30720
	ds_read_b64_tr_b16 v[54:55], v197 offset:31232
	v_mfma_f32_32x32x16_bf16 v[84:99], v[160:163], v[124:127], v[84:99]
	v_add_f32_e32 v80, v58, v80
	v_add_f32_e32 v80, v59, v80
	v_cvt_pk_bf16_f32 v56, v56, v57
	v_add_f32_e32 v80, v60, v80
	v_and_b32_e32 v142, v56, v196
	v_cvt_pk_bf16_f32 v56, v58, v59
	v_add_f32_e32 v80, v61, v80
	v_and_b32_e32 v143, v56, v196
	ds_read_b64_tr_b16 v[56:57], v197 offset:27648
	ds_read_b64_tr_b16 v[58:59], v197 offset:28160
	v_mfma_f32_32x32x16_bf16 v[100:115], v[156:159], v[128:131], v[100:115]
	v_add_f32_e32 v80, v62, v80
	v_add_f32_e32 v80, v63, v80
	v_cvt_pk_bf16_f32 v60, v60, v61
	v_add_f32_e32 v80, v64, v80
	v_and_b32_e32 v136, v60, v196
	v_cvt_pk_bf16_f32 v60, v62, v63
	v_add_f32_e32 v80, v65, v80
	v_and_b32_e32 v137, v60, v196
	ds_read_b64_tr_b16 v[60:61], v197 offset:31744
	ds_read_b64_tr_b16 v[62:63], v197 offset:32256
	v_mfma_f32_32x32x16_bf16 v[84:99], v[152:155], v[128:131], v[84:99]
	v_add_f32_e32 v80, v66, v80
	v_cvt_pk_bf16_f32 v64, v64, v65
	v_add_f32_e32 v80, v67, v80
	v_and_b32_e32 v138, v64, v196
	v_cvt_pk_bf16_f32 v64, v66, v67
	v_and_b32_e32 v139, v64, v196
	s_mov_b32 s22, 0xfffe0000
	s_mov_b32 s23, -1
	v_lshl_add_u64 v[64:65], v[194:195], 0, s[22:23]
	s_add_i32 s10, s25, s46
	s_mov_b32 m0, s10
	s_nop 0
	global_load_lds_dwordx4 v[64:65], off
	v_lshl_add_u64 v[64:65], v[192:193], 0, s[22:23]
	s_add_i32 s10, s24, s47
	s_mov_b32 m0, s10
	s_nop 0
	global_load_lds_dwordx4 v[64:65], off
	v_and_b32_e32 v66, v80, v196
	v_add_f32_e32 v204, v220, v66
.LBB0_799:
	s_waitcnt lgkmcnt(14)
	v_mfma_f32_32x32x16_bf16 v[20:35], v[148:151], v[184:187], v[20:35]
	v_exp_f32_e32 v100, v100
	v_exp_f32_e32 v101, v101
	v_exp_f32_e32 v102, v102
	v_exp_f32_e32 v103, v103
	s_waitcnt lgkmcnt(12)
	v_mfma_f32_32x32x16_bf16 v[4:19], v[148:151], v[180:183], v[4:19]
	v_exp_f32_e32 v104, v104
	v_exp_f32_e32 v105, v105
	v_exp_f32_e32 v106, v106
	v_exp_f32_e32 v107, v107
	v_add_u32_e32 v80, s24, v218
	ds_read_b128 v[64:67], v80
	ds_read_b128 v[180:183], v80 offset:512
	s_waitcnt lgkmcnt(12)
	v_mfma_f32_32x32x16_bf16 v[20:35], v[144:147], v[68:71], v[20:35]
	v_exp_f32_e32 v108, v108
	v_exp_f32_e32 v109, v109
	v_exp_f32_e32 v110, v110
	v_exp_f32_e32 v111, v111
	ds_read_b128 v[184:187], v80 offset:2048
	ds_read_b128 v[176:179], v80 offset:2560
	s_waitcnt lgkmcnt(12)
	v_mfma_f32_32x32x16_bf16 v[4:19], v[144:147], v[72:75], v[4:19]
	v_exp_f32_e32 v112, v112
	v_exp_f32_e32 v113, v113
	v_exp_f32_e32 v114, v114
	v_exp_f32_e32 v115, v115
	ds_read_b128 v[172:175], v80 offset:4096
	ds_read_b128 v[168:171], v80 offset:4608
	s_waitcnt lgkmcnt(12)
	v_mfma_f32_32x32x16_bf16 v[20:35], v[140:143], v[76:79], v[20:35]
	v_exp_f32_e32 v84, v84
	v_exp_f32_e32 v85, v85
	v_exp_f32_e32 v86, v86
	v_exp_f32_e32 v87, v87
	ds_read_b128 v[164:167], v80 offset:6144
	ds_read_b128 v[160:163], v80 offset:6656
	s_waitcnt lgkmcnt(12)
	v_mfma_f32_32x32x16_bf16 v[4:19], v[140:143], v[52:55], v[4:19]
	v_exp_f32_e32 v88, v88
	v_exp_f32_e32 v89, v89
	v_exp_f32_e32 v90, v90
	v_exp_f32_e32 v91, v91
	s_waitcnt lgkmcnt(10)
	v_mfma_f32_32x32x16_bf16 v[20:35], v[136:139], v[56:59], v[20:35]
	v_exp_f32_e32 v92, v92
	v_exp_f32_e32 v93, v93
	v_exp_f32_e32 v94, v94
	v_exp_f32_e32 v95, v95
	s_waitcnt lgkmcnt(8)
	v_mfma_f32_32x32x16_bf16 v[4:19], v[136:139], v[60:63], v[4:19]
	v_exp_f32_e32 v96, v96
	v_exp_f32_e32 v97, v97
	v_exp_f32_e32 v98, v98
	v_exp_f32_e32 v99, v99
	s_add_i32 s101, s101, 1
	s_add_i32 s10, s24, 0x2000
	s_cmpk_lg_i32 s24, 0x4000
	s_cselect_b32 s54, s10, 0
	s_waitcnt vmcnt(2) lgkmcnt(0)
	s_barrier
.LBB0_801:
	v_bfe_i32 v196, v132, s101, 1
	v_add_u32_e32 v197, s25, v219
	ds_read_b64_tr_b16 v[152:153], v197 offset:24576
	ds_read_b64_tr_b16 v[154:155], v197 offset:25088
	v_mfma_f32_32x32x16_bf16 v[68:83], v[64:67], v[116:119], v[36:51]
	v_add_f32_e32 v52, v100, v101
	v_add_f32_e32 v52, v102, v52
	v_add_f32_e32 v52, v103, v52
	v_cvt_pk_bf16_f32 v53, v100, v101
	v_add_f32_e32 v52, v104, v52
	v_and_b32_e32 v148, v53, v196
	v_cvt_pk_bf16_f32 v53, v102, v103
	v_add_f32_e32 v52, v105, v52
	v_and_b32_e32 v149, v53, v196
	ds_read_b64_tr_b16 v[156:157], v197 offset:28672
	ds_read_b64_tr_b16 v[158:159], v197 offset:29184
	v_add_f32_e32 v52, v106, v52
	v_add_f32_e32 v52, v107, v52
	v_add_f32_e32 v52, v108, v52
	v_add_f32_e32 v136, v109, v52
	v_mfma_f32_32x32x16_bf16 v[52:67], v[180:183], v[116:119], v[36:51]
	v_cvt_pk_bf16_f32 v100, v104, v105
	v_and_b32_e32 v150, v100, v196
	v_cvt_pk_bf16_f32 v100, v106, v107
	v_and_b32_e32 v151, v100, v196
	ds_read_b64_tr_b16 v[100:101], v197 offset:25600
	ds_read_b64_tr_b16 v[102:103], v197 offset:26112
	v_mfma_f32_32x32x16_bf16 v[68:83], v[184:187], v[120:123], v[68:83]
	v_add_f32_e32 v104, v110, v136
	v_add_f32_e32 v104, v111, v104
	v_add_f32_e32 v104, v112, v104
	v_add_f32_e32 v136, v113, v104
	v_cvt_pk_bf16_f32 v104, v108, v109
	v_and_b32_e32 v144, v104, v196
	v_cvt_pk_bf16_f32 v104, v110, v111
	v_and_b32_e32 v145, v104, v196
	ds_read_b64_tr_b16 v[104:105], v197 offset:29696
	ds_read_b64_tr_b16 v[106:107], v197 offset:30208
	v_mfma_f32_32x32x16_bf16 v[52:67], v[176:179], v[120:123], v[52:67]
	v_add_f32_e32 v108, v114, v136
	v_add_f32_e32 v108, v115, v108
	v_add_f32_e32 v108, v84, v108
	v_add_f32_e32 v136, v85, v108
	v_cvt_pk_bf16_f32 v108, v112, v113
	v_and_b32_e32 v146, v108, v196
	v_cvt_pk_bf16_f32 v108, v114, v115
	v_and_b32_e32 v147, v108, v196
	ds_read_b64_tr_b16 v[108:109], v197 offset:26624
	ds_read_b64_tr_b16 v[110:111], v197 offset:27136
	v_mfma_f32_32x32x16_bf16 v[68:83], v[172:175], v[124:127], v[68:83]
	v_add_f32_e32 v112, v86, v136
	v_add_f32_e32 v112, v87, v112
	v_cvt_pk_bf16_f32 v84, v84, v85
	v_add_f32_e32 v112, v88, v112
	v_and_b32_e32 v140, v84, v196
	v_cvt_pk_bf16_f32 v84, v86, v87
	v_add_f32_e32 v112, v89, v112
	v_and_b32_e32 v141, v84, v196
	ds_read_b64_tr_b16 v[84:85], v197 offset:30720
	ds_read_b64_tr_b16 v[86:87], v197 offset:31232
	v_mfma_f32_32x32x16_bf16 v[52:67], v[168:171], v[124:127], v[52:67]
	v_add_f32_e32 v112, v90, v112
	v_add_f32_e32 v112, v91, v112
	v_cvt_pk_bf16_f32 v88, v88, v89
	v_add_f32_e32 v112, v92, v112
	v_and_b32_e32 v142, v88, v196
	v_cvt_pk_bf16_f32 v88, v90, v91
	v_add_f32_e32 v112, v93, v112
	v_and_b32_e32 v143, v88, v196
	ds_read_b64_tr_b16 v[88:89], v197 offset:27648
	ds_read_b64_tr_b16 v[90:91], v197 offset:28160
	v_mfma_f32_32x32x16_bf16 v[68:83], v[164:167], v[128:131], v[68:83]
	v_add_f32_e32 v112, v94, v112
	v_add_f32_e32 v112, v95, v112
	v_cvt_pk_bf16_f32 v92, v92, v93
	v_add_f32_e32 v112, v96, v112
	v_and_b32_e32 v136, v92, v196
	v_cvt_pk_bf16_f32 v92, v94, v95
	v_add_f32_e32 v112, v97, v112
	v_and_b32_e32 v137, v92, v196
	ds_read_b64_tr_b16 v[92:93], v197 offset:31744
	ds_read_b64_tr_b16 v[94:95], v197 offset:32256
	v_mfma_f32_32x32x16_bf16 v[52:67], v[160:163], v[128:131], v[52:67]
	v_add_f32_e32 v112, v98, v112
	v_cvt_pk_bf16_f32 v96, v96, v97
	v_add_f32_e32 v112, v99, v112
	v_and_b32_e32 v138, v96, v196
	v_cvt_pk_bf16_f32 v96, v98, v99
	v_and_b32_e32 v139, v96, v196
	v_and_b32_e32 v96, v112, v196
	v_add_f32_e32 v220, v204, v96
	s_add_i32 s10, s24, s46
	s_mov_b32 m0, s10
	s_nop 0
	global_load_lds_dwordx4 v[194:195], off
	s_add_i32 s10, s54, s47
	s_mov_b32 m0, s10
	s_nop 0
	global_load_lds_dwordx4 v[192:193], off
.LBB0_802:
	s_waitcnt lgkmcnt(14)
	v_mfma_f32_32x32x16_bf16 v[20:35], v[148:151], v[152:155], v[20:35]
	v_exp_f32_e32 v68, v68
	v_exp_f32_e32 v69, v69
	v_exp_f32_e32 v70, v70
	v_exp_f32_e32 v71, v71
	s_waitcnt lgkmcnt(12)
	v_mfma_f32_32x32x16_bf16 v[4:19], v[148:151], v[156:159], v[4:19]
	v_exp_f32_e32 v72, v72
	v_exp_f32_e32 v73, v73
	v_exp_f32_e32 v74, v74
	v_exp_f32_e32 v75, v75
	v_add_u32_e32 v96, s54, v218
	ds_read_b128 v[180:183], v96
	ds_read_b128 v[176:179], v96 offset:512
	s_waitcnt lgkmcnt(12)
	v_mfma_f32_32x32x16_bf16 v[20:35], v[144:147], v[100:103], v[20:35]
	v_exp_f32_e32 v76, v76
	v_exp_f32_e32 v77, v77
	v_exp_f32_e32 v78, v78
	v_exp_f32_e32 v79, v79
	ds_read_b128 v[172:175], v96 offset:2048
	ds_read_b128 v[168:171], v96 offset:2560
	s_waitcnt lgkmcnt(12)
	v_mfma_f32_32x32x16_bf16 v[4:19], v[144:147], v[104:107], v[4:19]
	v_exp_f32_e32 v80, v80
	v_exp_f32_e32 v81, v81
	v_exp_f32_e32 v82, v82
	v_exp_f32_e32 v83, v83
	ds_read_b128 v[164:167], v96 offset:4096
	ds_read_b128 v[160:163], v96 offset:4608
	s_waitcnt lgkmcnt(12)
	v_mfma_f32_32x32x16_bf16 v[20:35], v[140:143], v[108:111], v[20:35]
	v_exp_f32_e32 v52, v52
	v_exp_f32_e32 v53, v53
	v_exp_f32_e32 v54, v54
	v_exp_f32_e32 v55, v55
	ds_read_b128 v[156:159], v96 offset:6144
	ds_read_b128 v[152:155], v96 offset:6656
	s_waitcnt lgkmcnt(12)
	v_mfma_f32_32x32x16_bf16 v[4:19], v[140:143], v[84:87], v[4:19]
	v_exp_f32_e32 v56, v56
	v_exp_f32_e32 v57, v57
	v_exp_f32_e32 v58, v58
	v_exp_f32_e32 v59, v59
	s_waitcnt lgkmcnt(10)
	v_mfma_f32_32x32x16_bf16 v[20:35], v[136:139], v[88:91], v[20:35]
	v_exp_f32_e32 v60, v60
	v_exp_f32_e32 v61, v61
	v_exp_f32_e32 v62, v62
	v_exp_f32_e32 v63, v63
	s_waitcnt lgkmcnt(8)
	v_mfma_f32_32x32x16_bf16 v[4:19], v[136:139], v[92:95], v[4:19]
	v_exp_f32_e32 v64, v64
	v_exp_f32_e32 v65, v65
	v_exp_f32_e32 v66, v66
	v_exp_f32_e32 v67, v67
	s_add_i32 s101, s101, 1
	s_cmp_eq_u32 s101, 32
	s_cbranch_scc1 .Lattn0_rot
.Lattn0_rotback:
	s_add_i32 s0, s0, 2
	s_add_i32 s10, s54, 0x2000
	s_cmpk_lg_i32 s54, 0x4000
	s_cselect_b32 s42, s10, 0
	v_lshl_add_u64 v[192:193], v[192:193], 0, s[80:81]
	s_cmp_ge_i32 s0, s1
	v_lshl_add_u64 v[194:195], v[194:195], 0, s[80:81]
	s_cbranch_scc1 .Lattn0_exit
	s_mov_b32 s10, s24
	s_mov_b32 s25, s54
	s_mov_b32 s24, s42
	s_branch .Lattn0_head
.Lattn0_exit:
	v_alignbit_b32 v132, v133, v132, s101
	v_alignbit_b32 v133, v134, v133, s101
	v_alignbit_b32 v134, v135, v134, s101
	v_lshrrev_b32_e32 v135, s101, v135
	s_waitcnt vmcnt(2) lgkmcnt(0)
	s_barrier
	s_branch .LBB0_813
.Lattn0_rot:
	v_mov_b32_e32 v132, v133
	v_mov_b32_e32 v133, v134
	v_mov_b32_e32 v134, v135
	v_mov_b32_e32 v135, 0
	s_mov_b32 s101, 0
	s_branch .Lattn0_rotback
